# baseline (speedup 1.0000x reference)
; __device__ __forceinline__ float partner_sum(float v) { auto rr = __builtin_amdgcn_permlane32_swap(__float_as_uint(v), __float_as_uint(v), false, false); return __uint_as_float(rr[0]) + __uint_as_float(rr[1]); }
; __device__ __forceinline__ void df_unit_p128(ATT_LAS unsigned char* lds, const bf16_t* Q, const bf16_t* __restrict__ K, const bf16_t* __restrict__ V, bf16_t* O, int b, int h, int qb,
;                                              float lam, float post, const float* __restrict__ sub_g, const int wv) {
;     ...
;     if (mp == 0) {
;         float ss = 0.f;
; #pragma unroll
;         for (int d0 = 0; d0 < 4; ++d0)
; #pragma unroll
;             for (int i = 0; i < 4; ++i) { const f32x4 x2 = xch[(d0 * 4 + i) * 64];
; #pragma unroll
;                 for (int jj = 0; jj < 4; ++jj) { const float v = o[d0][4 * i + jj] * inv - x2[jj]; o[d0][4 * i + jj] = v; ss += v * v; } }
;         ss = partner_sum(ss);
;         const float rs = __builtin_amdgcn_rsqf(ss * (1.0f / 128.0f) + 1e-6f) * post;
;         bf16_t* Ow = O + (rowbase + q0 + rg * 32 + r32e) * DM + h * 128 + 4 * hie;
; #pragma unroll
;         for (int d0 = 0; d0 < 4; ++d0)
; #pragma unroll
;             for (int i = 0; i < 4; ++i) { const f32x4 g = *(const f32x4*)(sub_g + d0 * 32 + 8 * i + 4 * hie);
.LBB0_233:
	s_andn2_b64 vcc, exec, s[8:9]
	s_waitcnt vmcnt(0) lgkmcnt(0)
	s_barrier
	s_cbranch_vccnz .LBB0_235
	v_ashrrev_i32_e32 v208, 3, v4
	v_and_b32_e32 v208, -4, v208
	v_ashrrev_i32_e32 v209, 31, v208
	v_lshl_add_u64 v[206:207], v[208:209], 2, s[0:1]
	global_load_dwordx4 v[130:133], v[206:207], off
	global_load_dwordx4 v[134:137], v[206:207], off offset:32
	global_load_dwordx4 v[138:141], v[206:207], off offset:64
	global_load_dwordx4 v[142:145], v[206:207], off offset:96
	global_load_dwordx4 v[146:149], v[206:207], off offset:128
	global_load_dwordx4 v[150:153], v[206:207], off offset:160
	global_load_dwordx4 v[154:157], v[206:207], off offset:192
	global_load_dwordx4 v[158:161], v[206:207], off offset:224
	global_load_dwordx4 v[162:165], v[206:207], off offset:256
	global_load_dwordx4 v[166:169], v[206:207], off offset:288
	global_load_dwordx4 v[170:173], v[206:207], off offset:320
	global_load_dwordx4 v[174:177], v[206:207], off offset:352
	global_load_dwordx4 v[178:181], v[206:207], off offset:384
	global_load_dwordx4 v[182:185], v[206:207], off offset:416
	global_load_dwordx4 v[186:189], v[206:207], off offset:448
	global_load_dwordx4 v[190:193], v[206:207], off offset:480
	ds_read_b128 v[6:9], v2
	s_waitcnt lgkmcnt(0)
	v_fma_f32 v37, v66, v0, -v6
	v_fma_f32 v34, v67, v0, -v7
	v_fma_f32 v35, v68, v0, -v8
	v_fma_f32 v36, v69, v0, -v9
	ds_read_b128 v[6:9], v2 offset:1024
	v_mul_f32_e32 v3, v34, v34
	v_fmac_f32_e32 v3, v37, v37
	v_fmac_f32_e32 v3, v35, v35
	v_fmac_f32_e32 v3, v36, v36
	s_waitcnt lgkmcnt(0)
	v_fma_f32 v50, v70, v0, -v6
	v_fma_f32 v51, v71, v0, -v7
	v_fma_f32 v52, v72, v0, -v8
	v_fma_f32 v53, v73, v0, -v9
	ds_read_b128 v[6:9], v2 offset:2048
	v_fmac_f32_e32 v3, v50, v50
	v_fmac_f32_e32 v3, v51, v51
	v_fmac_f32_e32 v3, v52, v52
	v_fmac_f32_e32 v3, v53, v53
	s_waitcnt lgkmcnt(0)
	v_fma_f32 v58, v74, v0, -v6
	v_fma_f32 v54, v75, v0, -v7
	v_fma_f32 v46, v76, v0, -v8
	v_fma_f32 v42, v77, v0, -v9
	ds_read_b128 v[6:9], v2 offset:3072
	v_fmac_f32_e32 v3, v58, v58
	v_fmac_f32_e32 v3, v54, v54
	v_fmac_f32_e32 v3, v46, v46
	v_fmac_f32_e32 v3, v42, v42
	s_waitcnt lgkmcnt(0)
	v_fma_f32 v71, v78, v0, -v6
	v_fma_f32 v68, v79, v0, -v7
	v_fma_f32 v65, v80, v0, -v8
	v_fma_f32 v62, v81, v0, -v9
	ds_read_b128 v[6:9], v2 offset:4096
	v_fmac_f32_e32 v3, v71, v71
	v_fmac_f32_e32 v3, v68, v68
	v_fmac_f32_e32 v3, v65, v65
	v_fmac_f32_e32 v3, v62, v62
	s_waitcnt lgkmcnt(0)
	v_fma_f32 v59, v82, v0, -v6
	v_fma_f32 v55, v83, v0, -v7
	v_fma_f32 v47, v84, v0, -v8
	v_fma_f32 v43, v85, v0, -v9
	ds_read_b128 v[6:9], v2 offset:5120
	v_fmac_f32_e32 v3, v59, v59
	v_fmac_f32_e32 v3, v55, v55
	v_fmac_f32_e32 v3, v47, v47
	v_fmac_f32_e32 v3, v43, v43
	s_waitcnt lgkmcnt(0)
	v_fma_f32 v72, v86, v0, -v6
	v_fma_f32 v69, v87, v0, -v7
	v_fma_f32 v66, v88, v0, -v8
	v_fma_f32 v63, v89, v0, -v9
	ds_read_b128 v[6:9], v2 offset:6144
	v_fmac_f32_e32 v3, v72, v72
	v_fmac_f32_e32 v3, v69, v69
	v_fmac_f32_e32 v3, v66, v66
	v_fmac_f32_e32 v3, v63, v63
	s_waitcnt lgkmcnt(0)
	v_fma_f32 v60, v90, v0, -v6
	v_fma_f32 v56, v91, v0, -v7
	v_fma_f32 v48, v92, v0, -v8
	v_fma_f32 v44, v93, v0, -v9
	ds_read_b128 v[6:9], v2 offset:7168
	v_fmac_f32_e32 v3, v60, v60
	v_fmac_f32_e32 v3, v56, v56
	v_fmac_f32_e32 v3, v48, v48
	v_fmac_f32_e32 v3, v44, v44
	s_waitcnt lgkmcnt(0)
	v_fma_f32 v73, v94, v0, -v6
	v_fma_f32 v70, v95, v0, -v7
	v_fma_f32 v67, v96, v0, -v8
	v_fma_f32 v64, v97, v0, -v9
	ds_read_b128 v[6:9], v2 offset:8192
	v_fmac_f32_e32 v3, v73, v73
	v_fmac_f32_e32 v3, v70, v70
	v_fmac_f32_e32 v3, v67, v67
	v_fmac_f32_e32 v3, v64, v64
	s_waitcnt lgkmcnt(0)
	v_fma_f32 v61, v98, v0, -v6
	v_fma_f32 v57, v99, v0, -v7
	v_fma_f32 v49, v100, v0, -v8
	v_fma_f32 v45, v101, v0, -v9
	ds_read_b128 v[6:9], v2 offset:9216
	v_fmac_f32_e32 v3, v61, v61
	v_fmac_f32_e32 v3, v57, v57
	v_fmac_f32_e32 v3, v49, v49
	v_fmac_f32_e32 v3, v45, v45
	s_waitcnt lgkmcnt(0)
	v_fma_f32 v41, v102, v0, -v6
	v_fma_f32 v40, v103, v0, -v7
	v_fma_f32 v39, v104, v0, -v8
	v_fma_f32 v38, v105, v0, -v9
	ds_read_b128 v[6:9], v2 offset:10240
	v_fmac_f32_e32 v3, v41, v41
	v_fmac_f32_e32 v3, v40, v40
	v_fmac_f32_e32 v3, v39, v39
	v_fmac_f32_e32 v3, v38, v38
	s_waitcnt lgkmcnt(0)
	v_fma_f32 v33, v106, v0, -v6
	v_fma_f32 v32, v107, v0, -v7
	v_fma_f32 v31, v108, v0, -v8
	v_fma_f32 v30, v109, v0, -v9
	ds_read_b128 v[6:9], v2 offset:11264
	v_fmac_f32_e32 v3, v33, v33
	v_fmac_f32_e32 v3, v32, v32
	v_fmac_f32_e32 v3, v31, v31
	v_fmac_f32_e32 v3, v30, v30
	s_waitcnt lgkmcnt(0)
	v_fma_f32 v29, v110, v0, -v6
	v_fma_f32 v28, v111, v0, -v7
	v_fma_f32 v27, v112, v0, -v8
	v_fma_f32 v26, v113, v0, -v9
	ds_read_b128 v[6:9], v2 offset:12288
	v_fmac_f32_e32 v3, v29, v29
	v_fmac_f32_e32 v3, v28, v28
	v_fmac_f32_e32 v3, v27, v27
	v_fmac_f32_e32 v3, v26, v26
	s_waitcnt lgkmcnt(0)
	v_fma_f32 v25, v114, v0, -v6
	v_fma_f32 v24, v115, v0, -v7
	v_fma_f32 v23, v116, v0, -v8
	v_fma_f32 v22, v117, v0, -v9
	ds_read_b128 v[6:9], v2 offset:13312
	v_fmac_f32_e32 v3, v25, v25
	v_fmac_f32_e32 v3, v24, v24
	v_fmac_f32_e32 v3, v23, v23
	v_fmac_f32_e32 v3, v22, v22
	s_waitcnt lgkmcnt(0)
	v_fma_f32 v21, v118, v0, -v6
	v_fma_f32 v20, v119, v0, -v7
	v_fma_f32 v19, v120, v0, -v8
	v_fma_f32 v18, v121, v0, -v9
	ds_read_b128 v[6:9], v2 offset:14336
	v_fmac_f32_e32 v3, v21, v21
	v_fmac_f32_e32 v3, v20, v20
	v_fmac_f32_e32 v3, v19, v19
	v_fmac_f32_e32 v3, v18, v18
	s_waitcnt lgkmcnt(0)
	v_fma_f32 v17, v122, v0, -v6
	v_fma_f32 v16, v123, v0, -v7
	v_fma_f32 v15, v124, v0, -v8
	v_fma_f32 v14, v125, v0, -v9
	ds_read_b128 v[6:9], v2 offset:15360
	v_fmac_f32_e32 v3, v17, v17
	v_fmac_f32_e32 v3, v16, v16
	v_fmac_f32_e32 v3, v15, v15
	v_fmac_f32_e32 v3, v14, v14
	s_waitcnt lgkmcnt(0)
; __device__ __forceinline__ unsigned cvtpk(float lo, float hi) { unsigned r; asm volatile("v_cvt_pk_bf16_f32 %0, %1, %2" : "=v"(r) : "v"(lo), "v"(hi)); return r; }
; __device__ __forceinline__ float partner_sum(float v) { auto rr = __builtin_amdgcn_permlane32_swap(__float_as_uint(v), __float_as_uint(v), false, false); return __uint_as_float(rr[0]) + __uint_as_float(rr[1]); }
; __device__ __forceinline__ void df_unit_p128(ATT_LAS unsigned char* lds, const bf16_t* Q, const bf16_t* __restrict__ K, const bf16_t* __restrict__ V, bf16_t* O, int b, int h, int qb,
;                                              float lam, float post, const float* __restrict__ sub_g, const int wv) {
;     ...
;             for (int i = 0; i < 4; ++i) { const f32x4 x2 = xch[(d0 * 4 + i) * 64];
; #pragma unroll
;                 for (int jj = 0; jj < 4; ++jj) { const float v = o[d0][4 * i + jj] * inv - x2[jj]; o[d0][4 * i + jj] = v; ss += v * v; } }
;         ss = partner_sum(ss);
;         const float rs = __builtin_amdgcn_rsqf(ss * (1.0f / 128.0f) + 1e-6f) * post;
;         bf16_t* Ow = O + (rowbase + q0 + rg * 32 + r32e) * DM + h * 128 + 4 * hie;
; #pragma unroll
;         for (int d0 = 0; d0 < 4; ++d0)
; #pragma unroll
;             for (int i = 0; i < 4; ++i) { const f32x4 g = *(const f32x4*)(sub_g + d0 * 32 + 8 * i + 4 * hie);
;                 u32x2 w; w.x = cvtpk(o[d0][4 * i] * rs * g[0], o[d0][4 * i + 1] * rs * g[1]); w.y = cvtpk(o[d0][4 * i + 2] * rs * g[2], o[d0][4 * i + 3] * rs * g[3]);
;                 *(u32x2*)(Ow + d0 * 32 + 8 * i) = w; }
	v_fma_f32 v13, v126, v0, -v6
	v_fmac_f32_e32 v3, v13, v13
	v_fma_f32 v12, v127, v0, -v7
	v_fmac_f32_e32 v3, v12, v12
	v_fma_f32 v10, v128, v0, -v8
	v_fmac_f32_e32 v3, v10, v10
	v_fma_f32 v0, v129, v0, -v9
	v_fmac_f32_e32 v3, v0, v0
	v_mov_b32_e32 v2, v3
	s_nop 1
	v_permlane32_swap_b32_e32 v3, v2
	v_add_f32_e32 v2, v3, v2
	v_fmamk_f32 v2, v2, 0x3c000000, v240
	v_rsq_f32_e32 v2, v2
	v_mov_b32_e32 v3, s27
	v_mul_f32_e32 v11, v245, v2
	v_and_or_b32 v2, v4, 31, s26
	v_ashrrev_i32_e32 v4, 3, v4
	v_lshlrev_b64 v[2:3], 11, v[2:3]
	v_and_b32_e32 v4, -4, v4
	v_lshl_add_u64 v[2:3], s[56:57], 0, v[2:3]
	v_ashrrev_i32_e32 v5, 31, v4
	v_lshl_add_u64 v[2:3], v[2:3], 0, s[54:55]
	v_lshl_add_u64 v[8:9], v[4:5], 2, s[0:1]
	v_lshl_add_u64 v[6:7], v[4:5], 1, v[2:3]
	v_mul_f32_e32 v37, v37, v11
	v_mul_f32_e32 v34, v34, v11
	v_mul_f32_e32 v33, v33, v11
	v_mul_f32_e32 v32, v32, v11
	v_mul_f32_e32 v29, v29, v11
	v_mul_f32_e32 v28, v28, v11
	v_mul_f32_e32 v25, v25, v11
	v_mul_f32_e32 v24, v24, v11
	v_mul_f32_e32 v21, v21, v11
	v_mul_f32_e32 v20, v20, v11
	v_mul_f32_e32 v17, v17, v11
	v_mul_f32_e32 v16, v16, v11
	v_mul_f32_e32 v0, v0, v11
	s_waitcnt vmcnt(0)
	v_mul_f32_e32 v2, v130, v37
	v_mul_f32_e32 v3, v131, v34
	v_cvt_pk_bf16_f32 v2, v2, v3
	v_mul_f32_e32 v3, v35, v11
	v_mul_f32_e32 v3, v132, v3
	v_mul_f32_e32 v4, v36, v11
	v_mul_f32_e32 v4, v133, v4
	v_cvt_pk_bf16_f32 v3, v3, v4
	global_store_dwordx2 v[6:7], v[2:3], off
	v_mul_f32_e32 v34, v50, v11
	v_mul_f32_e32 v2, v134, v34
	v_mul_f32_e32 v34, v51, v11
	v_mul_f32_e32 v3, v135, v34
	v_cvt_pk_bf16_f32 v2, v2, v3
	v_mul_f32_e32 v3, v52, v11
	v_mul_f32_e32 v3, v136, v3
	v_mul_f32_e32 v4, v53, v11
	v_mul_f32_e32 v4, v137, v4
	v_cvt_pk_bf16_f32 v3, v3, v4
	global_store_dwordx2 v[6:7], v[2:3], off offset:16
	v_mul_f32_e32 v34, v58, v11
	v_mul_f32_e32 v2, v34, v138
	v_mul_f32_e32 v34, v54, v11
	v_mul_f32_e32 v3, v34, v139
	v_cvt_pk_bf16_f32 v2, v2, v3
	v_mul_f32_e32 v3, v46, v11
	v_mul_f32_e32 v3, v3, v140
	v_mul_f32_e32 v4, v42, v11
	v_mul_f32_e32 v4, v4, v141
	v_cvt_pk_bf16_f32 v3, v3, v4
	global_store_dwordx2 v[6:7], v[2:3], off offset:32
	v_mul_f32_e32 v34, v71, v11
	v_mul_f32_e32 v2, v34, v142
	v_mul_f32_e32 v34, v68, v11
	v_mul_f32_e32 v3, v34, v143
	v_cvt_pk_bf16_f32 v2, v2, v3
	v_mul_f32_e32 v3, v65, v11
	v_mul_f32_e32 v3, v3, v144
	v_mul_f32_e32 v4, v62, v11
	v_mul_f32_e32 v4, v4, v145
	v_cvt_pk_bf16_f32 v3, v3, v4
	global_store_dwordx2 v[6:7], v[2:3], off offset:48
	v_mul_f32_e32 v34, v59, v11
	v_mul_f32_e32 v2, v34, v146
	v_mul_f32_e32 v34, v55, v11
	v_mul_f32_e32 v3, v34, v147
	v_cvt_pk_bf16_f32 v2, v2, v3
	v_mul_f32_e32 v3, v47, v11
	v_mul_f32_e32 v3, v3, v148
	v_mul_f32_e32 v4, v43, v11
	v_mul_f32_e32 v4, v4, v149
	v_cvt_pk_bf16_f32 v3, v3, v4
	global_store_dwordx2 v[6:7], v[2:3], off offset:64
	v_mul_f32_e32 v34, v72, v11
	v_mul_f32_e32 v2, v34, v150
	v_mul_f32_e32 v34, v69, v11
	v_mul_f32_e32 v3, v34, v151
	v_cvt_pk_bf16_f32 v2, v2, v3
	v_mul_f32_e32 v3, v66, v11
	v_mul_f32_e32 v3, v3, v152
	v_mul_f32_e32 v4, v63, v11
	v_mul_f32_e32 v4, v4, v153
	v_cvt_pk_bf16_f32 v3, v3, v4
	global_store_dwordx2 v[6:7], v[2:3], off offset:80
	v_mul_f32_e32 v34, v60, v11
	v_mul_f32_e32 v2, v34, v154
	v_mul_f32_e32 v34, v56, v11
	v_mul_f32_e32 v3, v34, v155
	v_cvt_pk_bf16_f32 v2, v2, v3
	v_mul_f32_e32 v3, v48, v11
	v_mul_f32_e32 v3, v3, v156
	v_mul_f32_e32 v4, v44, v11
	v_mul_f32_e32 v4, v4, v157
	v_cvt_pk_bf16_f32 v3, v3, v4
	global_store_dwordx2 v[6:7], v[2:3], off offset:96
	v_mul_f32_e32 v34, v73, v11
	v_mul_f32_e32 v2, v34, v158
	v_mul_f32_e32 v34, v70, v11
	v_mul_f32_e32 v3, v34, v159
	v_cvt_pk_bf16_f32 v2, v2, v3
	v_mul_f32_e32 v3, v67, v11
	v_mul_f32_e32 v3, v3, v160
	v_mul_f32_e32 v4, v64, v11
	v_mul_f32_e32 v4, v4, v161
	v_cvt_pk_bf16_f32 v3, v3, v4
	global_store_dwordx2 v[6:7], v[2:3], off offset:112
	v_mul_f32_e32 v34, v61, v11
	v_mul_f32_e32 v2, v34, v162
	v_mul_f32_e32 v34, v57, v11
	v_mul_f32_e32 v3, v34, v163
	v_cvt_pk_bf16_f32 v2, v2, v3
	v_mul_f32_e32 v3, v49, v11
	v_mul_f32_e32 v3, v3, v164
	v_mul_f32_e32 v4, v45, v11
	v_mul_f32_e32 v4, v4, v165
	v_cvt_pk_bf16_f32 v3, v3, v4
	global_store_dwordx2 v[6:7], v[2:3], off offset:128
	v_mul_f32_e32 v34, v41, v11
	v_mul_f32_e32 v2, v34, v166
	v_mul_f32_e32 v34, v40, v11
	v_mul_f32_e32 v3, v34, v167
	v_cvt_pk_bf16_f32 v2, v2, v3
	v_mul_f32_e32 v3, v39, v11
	v_mul_f32_e32 v3, v3, v168
	v_mul_f32_e32 v4, v38, v11
	v_mul_f32_e32 v4, v4, v169
	v_cvt_pk_bf16_f32 v3, v3, v4
	global_store_dwordx2 v[6:7], v[2:3], off offset:144
	v_mul_f32_e32 v2, v33, v170
	v_mul_f32_e32 v3, v32, v171
	v_cvt_pk_bf16_f32 v2, v2, v3
	v_mul_f32_e32 v3, v31, v11
	v_mul_f32_e32 v3, v3, v172
	v_mul_f32_e32 v4, v30, v11
	v_mul_f32_e32 v4, v4, v173
	v_cvt_pk_bf16_f32 v3, v3, v4
	global_store_dwordx2 v[6:7], v[2:3], off offset:160
	v_mul_f32_e32 v2, v29, v174
	v_mul_f32_e32 v3, v28, v175
	v_cvt_pk_bf16_f32 v2, v2, v3
	v_mul_f32_e32 v3, v27, v11
	v_mul_f32_e32 v3, v3, v176
	v_mul_f32_e32 v4, v26, v11
	v_mul_f32_e32 v4, v4, v177
	v_cvt_pk_bf16_f32 v3, v3, v4
	global_store_dwordx2 v[6:7], v[2:3], off offset:176
	v_mul_f32_e32 v2, v25, v178
	v_mul_f32_e32 v3, v24, v179
	v_cvt_pk_bf16_f32 v2, v2, v3
	v_mul_f32_e32 v3, v23, v11
	v_mul_f32_e32 v3, v3, v180
	v_mul_f32_e32 v4, v22, v11
	v_mul_f32_e32 v4, v4, v181
	v_cvt_pk_bf16_f32 v3, v3, v4
	global_store_dwordx2 v[6:7], v[2:3], off offset:192
	v_mul_f32_e32 v2, v21, v182
	v_mul_f32_e32 v3, v20, v183
	v_cvt_pk_bf16_f32 v2, v2, v3
	v_mul_f32_e32 v3, v19, v11
	v_mul_f32_e32 v3, v3, v184
	v_mul_f32_e32 v4, v18, v11
	v_mul_f32_e32 v4, v4, v185
	v_cvt_pk_bf16_f32 v3, v3, v4
	global_store_dwordx2 v[6:7], v[2:3], off offset:208
	v_mul_f32_e32 v2, v17, v186
	v_mul_f32_e32 v3, v16, v187
	v_cvt_pk_bf16_f32 v2, v2, v3
	v_mul_f32_e32 v3, v15, v11
	v_mul_f32_e32 v3, v3, v188
	v_mul_f32_e32 v4, v14, v11
	v_mul_f32_e32 v4, v4, v189
	v_cvt_pk_bf16_f32 v3, v3, v4
	global_store_dwordx2 v[6:7], v[2:3], off offset:224
	v_mul_f32_e32 v8, v13, v11
	v_mul_f32_e32 v2, v8, v190
	v_mul_f32_e32 v8, v12, v11
	v_mul_f32_e32 v3, v8, v191
	v_cvt_pk_bf16_f32 v2, v2, v3
	v_mul_f32_e32 v3, v10, v11
	v_mul_f32_e32 v3, v3, v192
	v_mul_f32_e32 v0, v0, v193
	v_cvt_pk_bf16_f32 v3, v3, v0
	global_store_dwordx2 v[6:7], v[2:3], off offset:240
